# merge pass output store non-temporal
# speedup vs baseline: 1.0081x; 1.0081x over previous
; __device__ __forceinline__ float bflo(unsigned u) { return __uint_as_float(u << 16); }
; __device__ __forceinline__ float bfhi(unsigned u) { return __uint_as_float(u & 0xffff0000u); }
; __device__ __forceinline__ unsigned pk2(float lo, float hi) { f32x2_t v = {lo, hi}; bf16x2_t b = __builtin_convertvector(v, bf16x2_t); return __builtin_bit_cast(unsigned, b); }
; __global__ void __launch_bounds__(NTHREADS, 2) fwd_megakernel(Args A) {
;     ...
;                 for (int i = bx * NTHREADS + tid; i < 8192 * 128; i += G * NTHREADS) {
;                     const int row = i >> 7, o8 = i & 127, h = o8 >> 3;
;                     const float l0 = LSE[((size_t)0 * 8192 + row) * 16 + h], l1 = LSE[((size_t)1 * 8192 + row) * 16 + h], l2 = LSE[((size_t)2 * 8192 + row) * 16 + h];
;                     const float mx = fmaxf(l0, fmaxf(l1, l2)); const float e0 = __expf(l0 - mx), e1 = __expf(l1 - mx), e2 = __expf(l2 - mx); const float inv = 1.f / (e0 + e1 + e2);
;                     const float w0 = e0 * inv, w1 = e1 * inv, w2 = e2 * inv;
;                     const size_t off = (size_t)row * DM + 8 * o8;
;                     const v4u a = *(const v4u*)(OG0 + off), b = *(const v4u*)(OG1 + off), c = *(const v4u*)(OG2 + off);
;                     v4u o;
;                     o.x = pk2(w0 * bflo(a.x) + w1 * bflo(b.x) + w2 * bflo(c.x), w0 * bfhi(a.x) + w1 * bfhi(b.x) + w2 * bfhi(c.x));
;                     o.y = pk2(w0 * bflo(a.y) + w1 * bflo(b.y) + w2 * bflo(c.y), w0 * bfhi(a.y) + w1 * bfhi(b.y) + w2 * bfhi(c.y));
;                     o.z = pk2(w0 * bflo(a.z) + w1 * bflo(b.z) + w2 * bflo(c.z), w0 * bfhi(a.z) + w1 * bfhi(b.z) + w2 * bfhi(c.z));
;                     o.w = pk2(w0 * bflo(a.w) + w1 * bflo(b.w) + w2 * bflo(c.w), w0 * bfhi(a.w) + w1 * bfhi(b.w) + w2 * bfhi(c.w));
;                     *(v4u*)(Y + (size_t)row_base * DM + off) = o;
;                 }
.LBB0_403:
	s_waitcnt vmcnt(3)
	v_ashrrev_i32_e32 v4, 7, v1
	v_ashrrev_i32_e32 v5, 31, v4
	v_lshlrev_b64 v[2:3], 6, v[4:5]
	v_lshl_add_u64 v[2:3], s[6:7], 0, v[2:3]
	v_mov_b32_e32 v147, v0
	v_lshl_add_u64 v[2:3], v[2:3], 0, v[146:147]
	v_add_co_u32_e32 v6, vcc, 0x80000, v2
	global_load_dword v8, v[2:3], off nt
	s_nop 0
	v_addc_co_u32_e32 v7, vcc, 0, v3, vcc
	global_load_dword v6, v[6:7], off nt
	v_add_co_u32_e32 v2, vcc, s21, v2
	v_lshlrev_b64 v[20:21], 11, v[4:5]
	s_nop 0
	v_addc_co_u32_e32 v3, vcc, 0, v3, vcc
	global_load_dword v2, v[2:3], off nt
	v_lshl_or_b32 v20, v144, 1, v20
	s_waitcnt vmcnt(5)
	v_lshl_add_u64 v[12:13], s[24:25], 0, v[20:21]
	global_load_dwordx4 v[12:15], v[12:13], off nt
	v_lshl_add_u64 v[4:5], s[80:81], 0, v[20:21]
	v_lshl_add_u64 v[26:27], s[8:9], 0, v[20:21]
	global_load_dwordx4 v[30:33], v[4:5], off nt
	global_load_dwordx4 v[34:37], v[26:27], off nt
	v_add_u32_e32 v1, s20, v1
	s_waitcnt vmcnt(3)
	v_max3_f32 v3, v8, v6, v2
	v_sub_f32_e32 v7, v8, v3
	v_sub_f32_e32 v6, v6, v3
	v_mul_f32_e32 v7, 0x3fb8aa3b, v7
	v_mul_f32_e32 v6, 0x3fb8aa3b, v6
	v_sub_f32_e32 v2, v2, v3
	v_exp_f32_e32 v17, v7
	v_exp_f32_e32 v16, v6
	v_mul_f32_e32 v2, 0x3fb8aa3b, v2
	v_exp_f32_e32 v2, v2
	s_waitcnt vmcnt(2)
	v_lshlrev_b32_e32 v24, 16, v12
	v_add_f32_e32 v3, v17, v16
	v_and_b32_e32 v25, 0xffff0000, v12
	v_add_f32_e32 v3, v2, v3
	v_div_scale_f32 v6, s[4:5], v3, v3, 1.0
	v_rcp_f32_e32 v7, v6
	v_lshlrev_b32_e32 v12, 16, v13
	v_and_b32_e32 v13, 0xffff0000, v13
	s_mov_b32 s4, 0xfffff
	v_fma_f32 v8, -v6, v7, 1.0
	v_fmac_f32_e32 v7, v8, v7
	v_div_scale_f32 v8, vcc, 1.0, v3, 1.0
	v_mul_f32_e32 v9, v8, v7
	v_fma_f32 v10, -v6, v9, v8
	v_fmac_f32_e32 v9, v10, v7
	v_fma_f32 v6, -v6, v9, v8
	v_div_fmas_f32 v6, v6, v7, v9
	v_div_fixup_f32 v18, v6, v3, 1.0
	v_pk_mul_f32 v[16:17], v[16:17], v[18:19] op_sel_hi:[1,0]
	v_mul_f32_e32 v2, v2, v18
	v_cmp_lt_i32_e32 vcc, s4, v1
	s_or_b64 s[2:3], vcc, s[2:3]
	s_waitcnt vmcnt(1)
	v_lshlrev_b32_e32 v22, 16, v30
	v_and_b32_e32 v19, 0xffff0000, v30
	s_waitcnt vmcnt(0)
	v_and_b32_e32 v23, 0xffff0000, v34
	v_lshlrev_b32_e32 v18, 16, v34
	v_pk_mul_f32 v[22:23], v[16:17], v[22:23] op_sel:[1,0] op_sel_hi:[0,1]
	v_pk_fma_f32 v[18:19], v[16:17], v[18:19], v[22:23]
	v_lshlrev_b32_e32 v34, 16, v31
	v_pk_fma_f32 v[18:19], v[2:3], v[24:25], v[18:19] op_sel_hi:[0,1,1]
	v_cvt_pk_bf16_f32 v30, v18, v19
	v_lshlrev_b32_e32 v18, 16, v35
	v_and_b32_e32 v35, 0xffff0000, v35
	v_and_b32_e32 v19, 0xffff0000, v31
	v_pk_mul_f32 v[34:35], v[16:17], v[34:35] op_sel:[1,0] op_sel_hi:[0,1]
	v_pk_fma_f32 v[34:35], v[16:17], v[18:19], v[34:35]
	v_lshlrev_b32_e32 v18, 16, v14
	v_pk_fma_f32 v[34:35], v[2:3], v[12:13], v[34:35] op_sel_hi:[0,1,1]
	v_lshlrev_b32_e32 v12, 16, v32
	v_and_b32_e32 v13, 0xffff0000, v36
	v_cvt_pk_bf16_f32 v31, v34, v35
	v_lshlrev_b32_e32 v34, 16, v36
	v_and_b32_e32 v35, 0xffff0000, v32
	v_pk_mul_f32 v[12:13], v[16:17], v[12:13] op_sel:[1,0] op_sel_hi:[0,1]
	v_and_b32_e32 v19, 0xffff0000, v14
	v_pk_fma_f32 v[34:35], v[16:17], v[34:35], v[12:13]
	v_lshlrev_b32_e32 v36, 16, v33
	v_pk_fma_f32 v[34:35], v[2:3], v[18:19], v[34:35] op_sel_hi:[0,1,1]
	v_cvt_pk_bf16_f32 v32, v34, v35
	v_lshlrev_b32_e32 v34, 16, v37
	v_and_b32_e32 v37, 0xffff0000, v37
	v_and_b32_e32 v35, 0xffff0000, v33
	v_pk_mul_f32 v[36:37], v[16:17], v[36:37] op_sel:[1,0] op_sel_hi:[0,1]
	v_pk_fma_f32 v[34:35], v[16:17], v[34:35], v[36:37]
	v_lshlrev_b32_e32 v36, 16, v15
	v_and_b32_e32 v37, 0xffff0000, v15
	v_pk_fma_f32 v[2:3], v[2:3], v[36:37], v[34:35] op_sel_hi:[0,1,1]
	v_cvt_pk_bf16_f32 v33, v2, v3
	v_lshl_add_u64 v[2:3], s[28:29], 0, v[20:21]
	global_store_dwordx4 v[2:3], v[30:33], off nt
	s_andn2_b64 exec, exec, s[2:3]
	s_cbranch_execnz .LBB0_403
